# swiglu epilogue: packed f32 mul/add + batched exp/rcp (8-element groups, no hazard nops); accumulator zeroing via v_mov_b64
# baseline (speedup 1.0000x reference)
;     ...
;         const bool has_next = S.next(ui + 1, nxt);
;         const char* nA = has_next ? (const char*)g.A + (size_t)nxt.pm * tstep + (size_t)nxt.k0 * 2 : cA; const char* nB = has_next ? (const char*)g.Bt + (size_t)nxt.pn * tstep + (size_t)nxt.k0 * 2 : cB;
;         const int nt = cur.nt;
;         for (int t = 0; t < nt; t += 2) {
;             const bool last = (t == nt - 2);
;             const char* a1 = cA + (size_t)(t + 1) * kstep;
;             const char* a2 = last ? nA : cA + (size_t)(t + 2) * kstep; const char* b2 = last ? nB : cB + (size_t)(t + 2) * kstep;
;             const char* a3 = a2 + kstep; const char* b3 = b2 + kstep;
;             if (last && has_next) S.a_ready(nxt);
;     ...
; #pragma unroll
;         for (int a = 0; a < 2; ++a)
; #pragma unroll
;             for (int b = 0; b < 2; ++b)
; #pragma unroll
;                 for (int m = 0; m < 4; ++m)
; #pragma unroll
;                     for (int n = 0; n < 2; ++n) acc[a][b][m][n] = (f32x4){0.f, 0.f, 0.f, 0.f};
.LBB0_564:
	s_ashr_i32 s11, s10, 31
	s_lshl_b64 s[16:17], s[10:11], 20
	s_add_u32 s16, s94, s16
	s_addc_u32 s17, s95, s17
	s_and_b64 s[18:19], s[14:15], exec
	s_cselect_b32 s11, s17, s23
	s_cselect_b32 s53, s16, s22
	s_ashr_i32 s13, s12, 31
	s_lshl_b64 s[18:19], s[12:13], 20
	s_add_u32 s18, s41, s18
	s_addc_u32 s19, s42, s19
	s_and_b64 s[24:25], s[14:15], exec
	s_cselect_b32 s13, s19, s21
	s_cselect_b32 s54, s18, s20
	s_cmp_gt_i32 s10, 31
	s_cselect_b64 s[24:25], -1, 0
	s_and_b32 s26, s10, 0xff
	s_or_b32 s55, s26, 0x600
	s_and_b64 s[26:27], s[0:1], s[14:15]
	s_mov_b32 s56, 0
	v_mov_b64_e32 v[2:3], 0
	v_mov_b64_e32 v[4:5], 0
	v_mov_b64_e32 v[6:7], 0
	v_mov_b64_e32 v[8:9], 0
	v_mov_b64_e32 v[10:11], 0
	v_mov_b64_e32 v[12:13], 0
	v_mov_b64_e32 v[14:15], 0
	v_mov_b64_e32 v[16:17], 0
	v_mov_b64_e32 v[18:19], 0
	v_mov_b64_e32 v[20:21], 0
	v_mov_b64_e32 v[22:23], 0
	v_mov_b64_e32 v[24:25], 0
	v_mov_b64_e32 v[26:27], 0
	v_mov_b64_e32 v[28:29], 0
	v_mov_b64_e32 v[30:31], 0
	v_mov_b64_e32 v[32:33], 0
	v_mov_b64_e32 v[34:35], 0
	v_mov_b64_e32 v[36:37], 0
	v_mov_b64_e32 v[38:39], 0
	v_mov_b64_e32 v[40:41], 0
	v_mov_b64_e32 v[42:43], 0
	v_mov_b64_e32 v[44:45], 0
	v_mov_b64_e32 v[46:47], 0
	v_mov_b64_e32 v[48:49], 0
	v_mov_b64_e32 v[50:51], 0
	v_mov_b64_e32 v[52:53], 0
	v_mov_b64_e32 v[54:55], 0
	v_mov_b64_e32 v[56:57], 0
	v_mov_b64_e32 v[58:59], 0
	v_mov_b64_e32 v[60:61], 0
	v_mov_b64_e32 v[62:63], 0
	v_mov_b64_e32 v[64:65], 0
	v_mov_b64_e32 v[66:67], 0
	v_mov_b64_e32 v[68:69], 0
	v_mov_b64_e32 v[70:71], 0
	v_mov_b64_e32 v[72:73], 0
	v_mov_b64_e32 v[74:75], 0
	v_mov_b64_e32 v[76:77], 0
	v_mov_b64_e32 v[78:79], 0
	v_mov_b64_e32 v[80:81], 0
	v_mov_b64_e32 v[82:83], 0
	v_mov_b64_e32 v[84:85], 0
	v_mov_b64_e32 v[86:87], 0
	v_mov_b64_e32 v[88:89], 0
	v_mov_b64_e32 v[90:91], 0
	v_mov_b64_e32 v[92:93], 0
	v_mov_b64_e32 v[94:95], 0
	v_mov_b64_e32 v[96:97], 0
	v_mov_b64_e32 v[98:99], 0
	v_mov_b64_e32 v[100:101], 0
	v_mov_b64_e32 v[102:103], 0
	v_mov_b64_e32 v[104:105], 0
	v_mov_b64_e32 v[106:107], 0
	v_mov_b64_e32 v[108:109], 0
	v_mov_b64_e32 v[110:111], 0
	v_mov_b64_e32 v[112:113], 0
	v_mov_b64_e32 v[114:115], 0
	v_mov_b64_e32 v[116:117], 0
	v_mov_b64_e32 v[118:119], 0
	v_mov_b64_e32 v[120:121], 0
	v_mov_b64_e32 v[122:123], 0
	v_mov_b64_e32 v[124:125], 0
	v_mov_b64_e32 v[126:127], 0
	v_mov_b64_e32 v[128:129], 0

; __device__ __forceinline__ unsigned cvt_pk_bf16(float lo, float hi) { unsigned r; asm volatile("v_cvt_pk_bf16_f32 %0, %1, %2" : "=v"(r) : "v"(lo), "v"(hi)); return r; }
;     __device__ __forceinline__ void operator()(const f32x4 (&acc)[2][2][4][2], const Unit& u, int wr, int wc, int fr, int fq) const {
;         if (skip) return;
;         const int row0 = u.pm * BM + wr * 64 + fr, col0 = u.pn * HALF + wc * 32 + 8 * fq;
; #pragma unroll
;         for (int ai = 0; ai < 2; ++ai)
; #pragma unroll
;             for (int m = 0; m < 4; ++m) { bf16_t* rowp = O + (size_t)(row0 + ai * HALF + m * 16) * ldc + col0;
;                 float v[8];
; #pragma unroll
;                 for (int n = 0; n < 2; ++n)
; #pragma unroll
;                     for (int j = 0; j < 4; ++j) { const float g = acc[ai][0][m][n][j], up = acc[ai][1][m][n][j];
;                         v[n * 4 + j] = g * __builtin_amdgcn_rcpf(1.0f + __expf(-g)) * up; }
;                 u32x4 w; w.x = cvt_pk_bf16(v[0], v[1]); w.y = cvt_pk_bf16(v[2], v[3]); w.z = cvt_pk_bf16(v[4], v[5]); w.w = cvt_pk_bf16(v[6], v[7]);
;                 if (NT_ACT) __builtin_nontemporal_store(w, (u32x4*)rowp); else *(u32x4*)rowp = w; }
.LBB0_586:
	v_mov_b32_e32 v150, 0xbfb8aa3b
	v_mov_b32_e32 v151, 0xbfb8aa3b
	v_mov_b32_e32 v152, 1.0
	v_mov_b32_e32 v153, 1.0
	v_pk_mul_f32 v[154:155], v[126:127], v[150:151]
	v_pk_mul_f32 v[156:157], v[128:129], v[150:151]
	v_pk_mul_f32 v[158:159], v[118:119], v[150:151]
	v_pk_mul_f32 v[160:161], v[120:121], v[150:151]
	v_exp_f32_e32 v154, v154
	v_exp_f32_e32 v155, v155
	v_exp_f32_e32 v156, v156
	v_exp_f32_e32 v157, v157
	v_exp_f32_e32 v158, v158
	v_exp_f32_e32 v159, v159
	v_exp_f32_e32 v160, v160
	v_exp_f32_e32 v161, v161
	v_pk_add_f32 v[154:155], v[154:155], v[152:153]
	v_pk_add_f32 v[156:157], v[156:157], v[152:153]
	v_pk_add_f32 v[158:159], v[158:159], v[152:153]
	v_pk_add_f32 v[160:161], v[160:161], v[152:153]
	v_rcp_f32_e32 v154, v154
	v_rcp_f32_e32 v155, v155
	v_rcp_f32_e32 v156, v156
	v_rcp_f32_e32 v157, v157
	v_rcp_f32_e32 v158, v158
	v_rcp_f32_e32 v159, v159
	v_rcp_f32_e32 v160, v160
	v_rcp_f32_e32 v161, v161
	v_pk_mul_f32 v[154:155], v[126:127], v[154:155]
	v_pk_mul_f32 v[156:157], v[128:129], v[156:157]
	v_pk_mul_f32 v[158:159], v[118:119], v[158:159]
	v_pk_mul_f32 v[160:161], v[120:121], v[160:161]
	v_pk_mul_f32 v[162:163], v[154:155], v[122:123]
	v_pk_mul_f32 v[164:165], v[156:157], v[124:125]
	v_pk_mul_f32 v[166:167], v[158:159], v[114:115]
	v_pk_mul_f32 v[168:169], v[160:161], v[116:117]
	v_lshl_or_b32 v146, s51, 7, v143
	v_lshl_add_u32 v145, s52, 8, v141
	v_ashrrev_i32_e32 v147, 31, v146
	v_mov_b64_e32 v[138:139], s[74:75]
	s_movk_i32 s11, 0x2c00
	v_mad_i64_i32 v[148:149], s[20:21], v145, s11, v[138:139]
	s_andn2_b64 vcc, exec, s[14:15]
	s_movk_i32 s25, 0x1600
	s_movk_i32 s24, 0x410
	v_lshlrev_b64 v[114:115], 1, v[146:147]
	v_lshl_add_u64 v[120:121], v[148:149], 0, v[114:115]
	v_cvt_pk_bf16_f32 v116, v162, v163
	v_cvt_pk_bf16_f32 v117, v164, v165
	v_cvt_pk_bf16_f32 v118, v166, v167
	v_cvt_pk_bf16_f32 v119, v168, v169
	global_store_dwordx4 v[120:121], v[116:119], off sc1
	v_pk_mul_f32 v[154:155], v[110:111], v[150:151]
	v_pk_mul_f32 v[156:157], v[112:113], v[150:151]
	v_pk_mul_f32 v[158:159], v[102:103], v[150:151]
	v_pk_mul_f32 v[160:161], v[104:105], v[150:151]
	v_exp_f32_e32 v154, v154
	v_exp_f32_e32 v155, v155
	v_exp_f32_e32 v156, v156
	v_exp_f32_e32 v157, v157
	v_exp_f32_e32 v158, v158
	v_exp_f32_e32 v159, v159
	v_exp_f32_e32 v160, v160
	v_exp_f32_e32 v161, v161
	v_pk_add_f32 v[154:155], v[154:155], v[152:153]
	v_pk_add_f32 v[156:157], v[156:157], v[152:153]
	v_pk_add_f32 v[158:159], v[158:159], v[152:153]
	v_pk_add_f32 v[160:161], v[160:161], v[152:153]
	v_rcp_f32_e32 v154, v154
	v_rcp_f32_e32 v155, v155
	v_rcp_f32_e32 v156, v156
	v_rcp_f32_e32 v157, v157
	v_rcp_f32_e32 v158, v158
	v_rcp_f32_e32 v159, v159
	v_rcp_f32_e32 v160, v160
	v_rcp_f32_e32 v161, v161
	v_pk_mul_f32 v[154:155], v[110:111], v[154:155]
	v_pk_mul_f32 v[156:157], v[112:113], v[156:157]
	v_pk_mul_f32 v[158:159], v[102:103], v[158:159]
	v_pk_mul_f32 v[160:161], v[104:105], v[160:161]
	v_pk_mul_f32 v[162:163], v[154:155], v[106:107]
	v_pk_mul_f32 v[164:165], v[156:157], v[108:109]
	v_pk_mul_f32 v[166:167], v[158:159], v[98:99]
	v_pk_mul_f32 v[168:169], v[160:161], v[100:101]
	v_or_b32_e32 v116, 16, v145
	v_mad_i64_i32 v[116:117], s[20:21], v116, s11, v[138:139]
	v_lshl_add_u64 v[102:103], v[116:117], 0, v[114:115]
	v_cvt_pk_bf16_f32 v98, v162, v163
	v_cvt_pk_bf16_f32 v99, v164, v165
	v_cvt_pk_bf16_f32 v100, v166, v167
	v_cvt_pk_bf16_f32 v101, v168, v169
	global_store_dwordx4 v[102:103], v[98:101], off sc1
	v_pk_mul_f32 v[154:155], v[94:95], v[150:151]
	v_pk_mul_f32 v[156:157], v[96:97], v[150:151]
	v_pk_mul_f32 v[158:159], v[86:87], v[150:151]
	v_pk_mul_f32 v[160:161], v[88:89], v[150:151]
	v_exp_f32_e32 v154, v154
	v_exp_f32_e32 v155, v155
	v_exp_f32_e32 v156, v156
	v_exp_f32_e32 v157, v157
	v_exp_f32_e32 v158, v158
	v_exp_f32_e32 v159, v159
	v_exp_f32_e32 v160, v160
	v_exp_f32_e32 v161, v161
	v_pk_add_f32 v[154:155], v[154:155], v[152:153]
	v_pk_add_f32 v[156:157], v[156:157], v[152:153]
	v_pk_add_f32 v[158:159], v[158:159], v[152:153]
	v_pk_add_f32 v[160:161], v[160:161], v[152:153]
	v_rcp_f32_e32 v154, v154
	v_rcp_f32_e32 v155, v155
	v_rcp_f32_e32 v156, v156
	v_rcp_f32_e32 v157, v157
	v_rcp_f32_e32 v158, v158
	v_rcp_f32_e32 v159, v159
	v_rcp_f32_e32 v160, v160
	v_rcp_f32_e32 v161, v161
	v_pk_mul_f32 v[154:155], v[94:95], v[154:155]
	v_pk_mul_f32 v[156:157], v[96:97], v[156:157]
	v_pk_mul_f32 v[158:159], v[86:87], v[158:159]
	v_pk_mul_f32 v[160:161], v[88:89], v[160:161]
	v_pk_mul_f32 v[162:163], v[154:155], v[90:91]
	v_pk_mul_f32 v[164:165], v[156:157], v[92:93]
	v_pk_mul_f32 v[166:167], v[158:159], v[82:83]
	v_pk_mul_f32 v[168:169], v[160:161], v[84:85]
	v_or_b32_e32 v98, 32, v145
	v_mad_i64_i32 v[98:99], s[20:21], v98, s11, v[138:139]
	v_lshl_add_u64 v[86:87], v[98:99], 0, v[114:115]
	v_cvt_pk_bf16_f32 v82, v162, v163
	v_cvt_pk_bf16_f32 v83, v164, v165
	v_cvt_pk_bf16_f32 v84, v166, v167
	v_cvt_pk_bf16_f32 v85, v168, v169
	global_store_dwordx4 v[86:87], v[82:85], off sc1
	v_pk_mul_f32 v[154:155], v[78:79], v[150:151]
	v_pk_mul_f32 v[156:157], v[80:81], v[150:151]
	v_pk_mul_f32 v[158:159], v[70:71], v[150:151]
	v_pk_mul_f32 v[160:161], v[72:73], v[150:151]
	v_exp_f32_e32 v154, v154
	v_exp_f32_e32 v155, v155
	v_exp_f32_e32 v156, v156
	v_exp_f32_e32 v157, v157
	v_exp_f32_e32 v158, v158
	v_exp_f32_e32 v159, v159
	v_exp_f32_e32 v160, v160
	v_exp_f32_e32 v161, v161
	v_pk_add_f32 v[154:155], v[154:155], v[152:153]
	v_pk_add_f32 v[156:157], v[156:157], v[152:153]
	v_pk_add_f32 v[158:159], v[158:159], v[152:153]
	v_pk_add_f32 v[160:161], v[160:161], v[152:153]
	v_rcp_f32_e32 v154, v154
	v_rcp_f32_e32 v155, v155
	v_rcp_f32_e32 v156, v156
	v_rcp_f32_e32 v157, v157
; __device__ __forceinline__ unsigned cvt_pk_bf16(float lo, float hi) { unsigned r; asm volatile("v_cvt_pk_bf16_f32 %0, %1, %2" : "=v"(r) : "v"(lo), "v"(hi)); return r; }
;     __device__ __forceinline__ void operator()(const f32x4 (&acc)[2][2][4][2], const Unit& u, int wr, int wc, int fr, int fq) const {
;         if (skip) return;
;         const int row0 = u.pm * BM + wr * 64 + fr, col0 = u.pn * HALF + wc * 32 + 8 * fq;
; #pragma unroll
;         for (int ai = 0; ai < 2; ++ai)
; #pragma unroll
;             for (int m = 0; m < 4; ++m) { bf16_t* rowp = O + (size_t)(row0 + ai * HALF + m * 16) * ldc + col0;
;                 float v[8];
; #pragma unroll
;                 for (int n = 0; n < 2; ++n)
; #pragma unroll
;                     for (int j = 0; j < 4; ++j) { const float g = acc[ai][0][m][n][j], up = acc[ai][1][m][n][j];
;                         v[n * 4 + j] = g * __builtin_amdgcn_rcpf(1.0f + __expf(-g)) * up; }
;                 u32x4 w; w.x = cvt_pk_bf16(v[0], v[1]); w.y = cvt_pk_bf16(v[2], v[3]); w.z = cvt_pk_bf16(v[4], v[5]); w.w = cvt_pk_bf16(v[6], v[7]);
;                 if (NT_ACT) __builtin_nontemporal_store(w, (u32x4*)rowp); else *(u32x4*)rowp = w; }
	v_rcp_f32_e32 v158, v158
	v_rcp_f32_e32 v159, v159
	v_rcp_f32_e32 v160, v160
	v_rcp_f32_e32 v161, v161
	v_pk_mul_f32 v[154:155], v[78:79], v[154:155]
	v_pk_mul_f32 v[156:157], v[80:81], v[156:157]
	v_pk_mul_f32 v[158:159], v[70:71], v[158:159]
	v_pk_mul_f32 v[160:161], v[72:73], v[160:161]
	v_pk_mul_f32 v[162:163], v[154:155], v[74:75]
	v_pk_mul_f32 v[164:165], v[156:157], v[76:77]
	v_pk_mul_f32 v[166:167], v[158:159], v[66:67]
	v_pk_mul_f32 v[168:169], v[160:161], v[68:69]
	v_or_b32_e32 v82, 48, v145
	v_mad_i64_i32 v[82:83], s[20:21], v82, s11, v[138:139]
	v_lshl_add_u64 v[70:71], v[82:83], 0, v[114:115]
	v_cvt_pk_bf16_f32 v66, v162, v163
	v_cvt_pk_bf16_f32 v67, v164, v165
	v_cvt_pk_bf16_f32 v68, v166, v167
	v_cvt_pk_bf16_f32 v69, v168, v169
	global_store_dwordx4 v[70:71], v[66:69], off sc1
	v_pk_mul_f32 v[154:155], v[62:63], v[150:151]
	v_pk_mul_f32 v[156:157], v[64:65], v[150:151]
	v_pk_mul_f32 v[158:159], v[54:55], v[150:151]
	v_pk_mul_f32 v[160:161], v[56:57], v[150:151]
	v_exp_f32_e32 v154, v154
	v_exp_f32_e32 v155, v155
	v_exp_f32_e32 v156, v156
	v_exp_f32_e32 v157, v157
	v_exp_f32_e32 v158, v158
	v_exp_f32_e32 v159, v159
	v_exp_f32_e32 v160, v160
	v_exp_f32_e32 v161, v161
	v_pk_add_f32 v[154:155], v[154:155], v[152:153]
	v_pk_add_f32 v[156:157], v[156:157], v[152:153]
	v_pk_add_f32 v[158:159], v[158:159], v[152:153]
	v_pk_add_f32 v[160:161], v[160:161], v[152:153]
	v_rcp_f32_e32 v154, v154
	v_rcp_f32_e32 v155, v155
	v_rcp_f32_e32 v156, v156
	v_rcp_f32_e32 v157, v157
	v_rcp_f32_e32 v158, v158
	v_rcp_f32_e32 v159, v159
	v_rcp_f32_e32 v160, v160
	v_rcp_f32_e32 v161, v161
	v_pk_mul_f32 v[154:155], v[62:63], v[154:155]
	v_pk_mul_f32 v[156:157], v[64:65], v[156:157]
	v_pk_mul_f32 v[158:159], v[54:55], v[158:159]
	v_pk_mul_f32 v[160:161], v[56:57], v[160:161]
	v_pk_mul_f32 v[162:163], v[154:155], v[58:59]
	v_pk_mul_f32 v[164:165], v[156:157], v[60:61]
	v_pk_mul_f32 v[166:167], v[158:159], v[50:51]
	v_pk_mul_f32 v[168:169], v[160:161], v[52:53]
	v_add_u32_e32 v66, 0x80, v145
	v_mad_i64_i32 v[66:67], s[20:21], v66, s11, v[138:139]
	v_lshl_add_u64 v[54:55], v[66:67], 0, v[114:115]
	v_cvt_pk_bf16_f32 v50, v162, v163
	v_cvt_pk_bf16_f32 v51, v164, v165
	v_cvt_pk_bf16_f32 v52, v166, v167
	v_cvt_pk_bf16_f32 v53, v168, v169
	global_store_dwordx4 v[54:55], v[50:53], off sc1
	v_pk_mul_f32 v[154:155], v[46:47], v[150:151]
	v_pk_mul_f32 v[156:157], v[48:49], v[150:151]
	v_pk_mul_f32 v[158:159], v[38:39], v[150:151]
	v_pk_mul_f32 v[160:161], v[40:41], v[150:151]
	v_exp_f32_e32 v154, v154
	v_exp_f32_e32 v155, v155
	v_exp_f32_e32 v156, v156
	v_exp_f32_e32 v157, v157
	v_exp_f32_e32 v158, v158
	v_exp_f32_e32 v159, v159
	v_exp_f32_e32 v160, v160
	v_exp_f32_e32 v161, v161
	v_pk_add_f32 v[154:155], v[154:155], v[152:153]
	v_pk_add_f32 v[156:157], v[156:157], v[152:153]
	v_pk_add_f32 v[158:159], v[158:159], v[152:153]
	v_pk_add_f32 v[160:161], v[160:161], v[152:153]
	v_rcp_f32_e32 v154, v154
	v_rcp_f32_e32 v155, v155
	v_rcp_f32_e32 v156, v156
	v_rcp_f32_e32 v157, v157
	v_rcp_f32_e32 v158, v158
	v_rcp_f32_e32 v159, v159
	v_rcp_f32_e32 v160, v160
	v_rcp_f32_e32 v161, v161
	v_pk_mul_f32 v[154:155], v[46:47], v[154:155]
	v_pk_mul_f32 v[156:157], v[48:49], v[156:157]
	v_pk_mul_f32 v[158:159], v[38:39], v[158:159]
	v_pk_mul_f32 v[160:161], v[40:41], v[160:161]
	v_pk_mul_f32 v[162:163], v[154:155], v[42:43]
	v_pk_mul_f32 v[164:165], v[156:157], v[44:45]
	v_pk_mul_f32 v[166:167], v[158:159], v[34:35]
	v_pk_mul_f32 v[168:169], v[160:161], v[36:37]
	v_add_u32_e32 v50, 0x90, v145
	v_mad_i64_i32 v[50:51], s[20:21], v50, s11, v[138:139]
	v_lshl_add_u64 v[38:39], v[50:51], 0, v[114:115]
	v_cvt_pk_bf16_f32 v34, v162, v163
	v_cvt_pk_bf16_f32 v35, v164, v165
	v_cvt_pk_bf16_f32 v36, v166, v167
	v_cvt_pk_bf16_f32 v37, v168, v169
	global_store_dwordx4 v[38:39], v[34:37], off sc1
	v_pk_mul_f32 v[154:155], v[30:31], v[150:151]
	v_pk_mul_f32 v[156:157], v[32:33], v[150:151]
	v_pk_mul_f32 v[158:159], v[22:23], v[150:151]
	v_pk_mul_f32 v[160:161], v[24:25], v[150:151]
	v_exp_f32_e32 v154, v154
	v_exp_f32_e32 v155, v155
	v_exp_f32_e32 v156, v156
	v_exp_f32_e32 v157, v157
	v_exp_f32_e32 v158, v158
	v_exp_f32_e32 v159, v159
	v_exp_f32_e32 v160, v160
	v_exp_f32_e32 v161, v161
	v_pk_add_f32 v[154:155], v[154:155], v[152:153]
	v_pk_add_f32 v[156:157], v[156:157], v[152:153]
	v_pk_add_f32 v[158:159], v[158:159], v[152:153]
	v_pk_add_f32 v[160:161], v[160:161], v[152:153]
	v_rcp_f32_e32 v154, v154
	v_rcp_f32_e32 v155, v155
	v_rcp_f32_e32 v156, v156
	v_rcp_f32_e32 v157, v157
	v_rcp_f32_e32 v158, v158
	v_rcp_f32_e32 v159, v159
	v_rcp_f32_e32 v160, v160
	v_rcp_f32_e32 v161, v161
	v_pk_mul_f32 v[154:155], v[30:31], v[154:155]
	v_pk_mul_f32 v[156:157], v[32:33], v[156:157]
	v_pk_mul_f32 v[158:159], v[22:23], v[158:159]
	v_pk_mul_f32 v[160:161], v[24:25], v[160:161]
	v_pk_mul_f32 v[162:163], v[154:155], v[26:27]
	v_pk_mul_f32 v[164:165], v[156:157], v[28:29]
	v_pk_mul_f32 v[166:167], v[158:159], v[18:19]
	v_pk_mul_f32 v[168:169], v[160:161], v[20:21]
	v_add_u32_e32 v34, 0xa0, v145
	v_mad_i64_i32 v[34:35], s[20:21], v34, s11, v[138:139]
	v_lshl_add_u64 v[22:23], v[34:35], 0, v[114:115]
	v_cvt_pk_bf16_f32 v18, v162, v163
	v_cvt_pk_bf16_f32 v19, v164, v165
	v_cvt_pk_bf16_f32 v20, v166, v167
	v_cvt_pk_bf16_f32 v21, v168, v169
	global_store_dwordx4 v[22:23], v[18:21], off sc1
	v_pk_mul_f32 v[154:155], v[14:15], v[150:151]
	v_pk_mul_f32 v[156:157], v[16:17], v[150:151]
	v_pk_mul_f32 v[158:159], v[6:7], v[150:151]
	v_pk_mul_f32 v[160:161], v[8:9], v[150:151]
	v_exp_f32_e32 v154, v154
	v_exp_f32_e32 v155, v155
	v_exp_f32_e32 v156, v156
	v_exp_f32_e32 v157, v157
	v_exp_f32_e32 v158, v158
	v_exp_f32_e32 v159, v159
	v_exp_f32_e32 v160, v160
	v_exp_f32_e32 v161, v161
	v_pk_add_f32 v[154:155], v[154:155], v[152:153]
	v_pk_add_f32 v[156:157], v[156:157], v[152:153]
	v_pk_add_f32 v[158:159], v[158:159], v[152:153]
	v_pk_add_f32 v[160:161], v[160:161], v[152:153]
	v_rcp_f32_e32 v154, v154
	v_rcp_f32_e32 v155, v155
	v_rcp_f32_e32 v156, v156
	v_rcp_f32_e32 v157, v157
	v_rcp_f32_e32 v158, v158
	v_rcp_f32_e32 v159, v159
	v_rcp_f32_e32 v160, v160
	v_rcp_f32_e32 v161, v161
	v_pk_mul_f32 v[154:155], v[14:15], v[154:155]
	v_pk_mul_f32 v[156:157], v[16:17], v[156:157]
	v_pk_mul_f32 v[158:159], v[6:7], v[158:159]
	v_pk_mul_f32 v[160:161], v[8:9], v[160:161]
	v_pk_mul_f32 v[162:163], v[154:155], v[10:11]
	v_pk_mul_f32 v[164:165], v[156:157], v[12:13]
	v_pk_mul_f32 v[166:167], v[158:159], v[2:3]
	v_pk_mul_f32 v[168:169], v[160:161], v[4:5]
	v_add_u32_e32 v18, 0xb0, v145
	v_mad_i64_i32 v[18:19], s[20:21], v18, s11, v[138:139]
	s_mov_b64 s[20:21], -1
	v_lshl_add_u64 v[6:7], v[18:19], 0, v[114:115]
	v_cvt_pk_bf16_f32 v2, v162, v163
	v_cvt_pk_bf16_f32 v3, v164, v165
	v_cvt_pk_bf16_f32 v4, v166, v167
	v_cvt_pk_bf16_f32 v5, v168, v169
	global_store_dwordx4 v[6:7], v[2:5], off sc1
	s_cbranch_vccnz .LBB0_557
	s_andn2_b64 vcc, exec, s[6:7]
	s_cbranch_vccnz .LBB0_556
	s_barrier
	s_branch .LBB0_556

;     ...
; #pragma unroll
;         for (int a = 0; a < 2; ++a)
; #pragma unroll
;             for (int b = 0; b < 2; ++b)
; #pragma unroll
;                 for (int m = 0; m < 4; ++m)
; #pragma unroll
;                     for (int n = 0; n < 2; ++n) acc[a][b][m][n] = (f32x4){0.f, 0.f, 0.f, 0.f};
;         cur = nxt; cA = nA; cB = nB; ++ui;
.LBB0_815:
	s_nop 0
	s_mov_b32 s10, s47
	s_mov_b32 s11, s48
	s_mov_b32 s8, s49
	s_mov_b32 s30, s50
	s_andn2_b64 vcc, exec, s[0:1]
	v_mov_b64_e32 v[2:3], 0
	v_mov_b64_e32 v[4:5], 0
	v_mov_b64_e32 v[6:7], 0
	v_mov_b64_e32 v[8:9], 0
	v_mov_b64_e32 v[10:11], 0
	v_mov_b64_e32 v[12:13], 0
	v_mov_b64_e32 v[14:15], 0
	v_mov_b64_e32 v[16:17], 0
	v_mov_b64_e32 v[18:19], 0
	v_mov_b64_e32 v[20:21], 0
	v_mov_b64_e32 v[22:23], 0
	v_mov_b64_e32 v[24:25], 0
	v_mov_b64_e32 v[26:27], 0
	v_mov_b64_e32 v[28:29], 0
	v_mov_b64_e32 v[30:31], 0
	v_mov_b64_e32 v[32:33], 0
	v_mov_b64_e32 v[34:35], 0
	v_mov_b64_e32 v[36:37], 0
	v_mov_b64_e32 v[38:39], 0
	v_mov_b64_e32 v[40:41], 0
	v_mov_b64_e32 v[42:43], 0
	v_mov_b64_e32 v[44:45], 0
	v_mov_b64_e32 v[46:47], 0
	v_mov_b64_e32 v[48:49], 0
	v_mov_b64_e32 v[50:51], 0
	v_mov_b64_e32 v[52:53], 0
	v_mov_b64_e32 v[54:55], 0
	v_mov_b64_e32 v[56:57], 0
	v_mov_b64_e32 v[58:59], 0
	v_mov_b64_e32 v[60:61], 0
	v_mov_b64_e32 v[62:63], 0
	v_mov_b64_e32 v[64:65], 0
	v_mov_b64_e32 v[66:67], 0
	v_mov_b64_e32 v[68:69], 0
	v_mov_b64_e32 v[70:71], 0
	v_mov_b64_e32 v[72:73], 0
	v_mov_b64_e32 v[74:75], 0
	v_mov_b64_e32 v[76:77], 0
	v_mov_b64_e32 v[78:79], 0
	v_mov_b64_e32 v[80:81], 0
	v_mov_b64_e32 v[82:83], 0
	v_mov_b64_e32 v[84:85], 0
	v_mov_b64_e32 v[86:87], 0
	v_mov_b64_e32 v[88:89], 0
	v_mov_b64_e32 v[90:91], 0
	v_mov_b64_e32 v[92:93], 0
	v_mov_b64_e32 v[94:95], 0
	v_mov_b64_e32 v[96:97], 0
	v_mov_b64_e32 v[98:99], 0
	v_mov_b64_e32 v[100:101], 0
	v_mov_b64_e32 v[102:103], 0
	v_mov_b64_e32 v[104:105], 0
	v_mov_b64_e32 v[106:107], 0
	v_mov_b64_e32 v[108:109], 0
	v_mov_b64_e32 v[110:111], 0
	v_mov_b64_e32 v[112:113], 0
	v_mov_b64_e32 v[114:115], 0
	v_mov_b64_e32 v[116:117], 0
	v_mov_b64_e32 v[118:119], 0
	v_mov_b64_e32 v[120:121], 0
	v_mov_b64_e32 v[122:123], 0
	v_mov_b64_e32 v[124:125], 0
	v_mov_b64_e32 v[126:127], 0
	v_mov_b64_e32 v[128:129], 0
	s_cbranch_vccnz .LBB0_801

; #define PG8_BAR __builtin_amdgcn_s_barrier()
;     ...
; #pragma unroll
;         for (int a = 0; a < 2; ++a)
; #pragma unroll
;             for (int b = 0; b < 2; ++b)
; #pragma unroll
;                 for (int m = 0; m < 4; ++m)
; #pragma unroll
;                     for (int n = 0; n < 2; ++n) acc[a][b][m][n] = (f32x4){0.f, 0.f, 0.f, 0.f};
;         cur = nxt; cA = nA; cB = nB; ++ui;
;         if constexpr (ALIGN_EPI) { if (wr == 1) PG8_BAR; }
.LBB0_1067:
	s_mov_b32 s50, s14
	s_mov_b32 s52, s10
	s_mov_b64 s[4:5], s[20:21]
	s_mov_b64 s[12:13], s[18:19]
	s_mov_b32 s51, s53
	v_mov_b64_e32 v[2:3], 0
	v_mov_b64_e32 v[4:5], 0
	v_mov_b64_e32 v[6:7], 0
	v_mov_b64_e32 v[8:9], 0
	v_mov_b64_e32 v[10:11], 0
	v_mov_b64_e32 v[12:13], 0
	v_mov_b64_e32 v[14:15], 0
	v_mov_b64_e32 v[16:17], 0
	v_mov_b64_e32 v[18:19], 0
	v_mov_b64_e32 v[20:21], 0
	v_mov_b64_e32 v[22:23], 0
	v_mov_b64_e32 v[24:25], 0
	v_mov_b64_e32 v[26:27], 0
	v_mov_b64_e32 v[28:29], 0
	v_mov_b64_e32 v[30:31], 0
	v_mov_b64_e32 v[32:33], 0
	v_mov_b64_e32 v[34:35], 0
	v_mov_b64_e32 v[36:37], 0
	v_mov_b64_e32 v[38:39], 0
	v_mov_b64_e32 v[40:41], 0
	v_mov_b64_e32 v[42:43], 0
	v_mov_b64_e32 v[44:45], 0
	v_mov_b64_e32 v[46:47], 0
	v_mov_b64_e32 v[48:49], 0
	v_mov_b64_e32 v[50:51], 0
	v_mov_b64_e32 v[52:53], 0
	v_mov_b64_e32 v[54:55], 0
	v_mov_b64_e32 v[56:57], 0
	v_mov_b64_e32 v[58:59], 0
	v_mov_b64_e32 v[60:61], 0
	v_mov_b64_e32 v[62:63], 0
	v_mov_b64_e32 v[64:65], 0
	v_mov_b64_e32 v[66:67], 0
	v_mov_b64_e32 v[68:69], 0
	v_mov_b64_e32 v[70:71], 0
	v_mov_b64_e32 v[72:73], 0
	v_mov_b64_e32 v[74:75], 0
	v_mov_b64_e32 v[76:77], 0
	v_mov_b64_e32 v[78:79], 0
	v_mov_b64_e32 v[80:81], 0
	v_mov_b64_e32 v[82:83], 0
	v_mov_b64_e32 v[84:85], 0
	v_mov_b64_e32 v[86:87], 0
	v_mov_b64_e32 v[88:89], 0
	v_mov_b64_e32 v[90:91], 0
	v_mov_b64_e32 v[92:93], 0
	v_mov_b64_e32 v[94:95], 0
	v_mov_b64_e32 v[96:97], 0
	v_mov_b64_e32 v[98:99], 0
	v_mov_b64_e32 v[100:101], 0
	v_mov_b64_e32 v[102:103], 0
	v_mov_b64_e32 v[104:105], 0
	v_mov_b64_e32 v[106:107], 0
	v_mov_b64_e32 v[108:109], 0
	v_mov_b64_e32 v[110:111], 0
	v_mov_b64_e32 v[112:113], 0
	v_mov_b64_e32 v[114:115], 0
	v_mov_b64_e32 v[116:117], 0
	v_mov_b64_e32 v[118:119], 0
	v_mov_b64_e32 v[120:121], 0
	v_mov_b64_e32 v[122:123], 0
	v_mov_b64_e32 v[124:125], 0
	v_mov_b64_e32 v[126:127], 0
	v_mov_b64_e32 v[128:129], 0

;     ...
; #pragma unroll
;         for (int a = 0; a < 2; ++a)
; #pragma unroll
;             for (int b = 0; b < 2; ++b)
; #pragma unroll
;                 for (int m = 0; m < 4; ++m)
; #pragma unroll
;                     for (int n = 0; n < 2; ++n) acc[a][b][m][n] = (f32x4){0.f, 0.f, 0.f, 0.f};
;         cur = nxt; cA = nA; cB = nB; ++ui;
.LBB0_1803:
	s_nop 0
	s_mov_b32 s12, s54
	s_mov_b32 s13, s55
	s_mov_b32 s4, s16
	s_mov_b32 s0, s18
	s_andn2_b64 vcc, exec, s[20:21]
	v_mov_b64_e32 v[2:3], 0
	v_mov_b64_e32 v[4:5], 0
	v_mov_b64_e32 v[6:7], 0
	v_mov_b64_e32 v[8:9], 0
	v_mov_b64_e32 v[10:11], 0
	v_mov_b64_e32 v[12:13], 0
	v_mov_b64_e32 v[14:15], 0
	v_mov_b64_e32 v[16:17], 0
	v_mov_b64_e32 v[18:19], 0
	v_mov_b64_e32 v[20:21], 0
	v_mov_b64_e32 v[22:23], 0
	v_mov_b64_e32 v[24:25], 0
	v_mov_b64_e32 v[26:27], 0
	v_mov_b64_e32 v[28:29], 0
	v_mov_b64_e32 v[30:31], 0
	v_mov_b64_e32 v[32:33], 0
	v_mov_b64_e32 v[34:35], 0
	v_mov_b64_e32 v[36:37], 0
	v_mov_b64_e32 v[38:39], 0
	v_mov_b64_e32 v[40:41], 0
	v_mov_b64_e32 v[42:43], 0
	v_mov_b64_e32 v[44:45], 0
	v_mov_b64_e32 v[46:47], 0
	v_mov_b64_e32 v[48:49], 0
	v_mov_b64_e32 v[50:51], 0
	v_mov_b64_e32 v[52:53], 0
	v_mov_b64_e32 v[54:55], 0
	v_mov_b64_e32 v[56:57], 0
	v_mov_b64_e32 v[58:59], 0
	v_mov_b64_e32 v[60:61], 0
	v_mov_b64_e32 v[62:63], 0
	v_mov_b64_e32 v[64:65], 0
	v_mov_b64_e32 v[66:67], 0
	v_mov_b64_e32 v[68:69], 0
	v_mov_b64_e32 v[70:71], 0
	v_mov_b64_e32 v[72:73], 0
	v_mov_b64_e32 v[74:75], 0
	v_mov_b64_e32 v[76:77], 0
	v_mov_b64_e32 v[78:79], 0
	v_mov_b64_e32 v[80:81], 0
	v_mov_b64_e32 v[82:83], 0
	v_mov_b64_e32 v[84:85], 0
	v_mov_b64_e32 v[86:87], 0
	v_mov_b64_e32 v[88:89], 0
	v_mov_b64_e32 v[90:91], 0
	v_mov_b64_e32 v[92:93], 0
	v_mov_b64_e32 v[94:95], 0
	v_mov_b64_e32 v[96:97], 0
	v_mov_b64_e32 v[98:99], 0
	v_mov_b64_e32 v[100:101], 0
	v_mov_b64_e32 v[102:103], 0
	v_mov_b64_e32 v[104:105], 0
	v_mov_b64_e32 v[106:107], 0
	v_mov_b64_e32 v[108:109], 0
	v_mov_b64_e32 v[110:111], 0
	v_mov_b64_e32 v[112:113], 0
	v_mov_b64_e32 v[114:115], 0
	v_mov_b64_e32 v[116:117], 0
	v_mov_b64_e32 v[118:119], 0
	v_mov_b64_e32 v[120:121], 0
	v_mov_b64_e32 v[122:123], 0
	v_mov_b64_e32 v[124:125], 0
	v_mov_b64_e32 v[126:127], 0
	v_mov_b64_e32 v[128:129], 0
	s_cbranch_vccnz .LBB0_1793

;     ...
; #pragma unroll
;         for (int a = 0; a < 2; ++a)
; #pragma unroll
;             for (int b = 0; b < 2; ++b)
; #pragma unroll
;                 for (int m = 0; m < 4; ++m)
; #pragma unroll
;                     for (int n = 0; n < 2; ++n) acc[a][b][m][n] = (f32x4){0.f, 0.f, 0.f, 0.f};
;         cur = nxt; cA = nA; cB = nB; ++ui;
.LBB0_2334:
	s_nop 0
	s_mov_b32 s20, s53
	s_mov_b32 s21, s54
	s_mov_b32 s10, s55
	s_mov_b32 s48, s56
	s_andn2_b64 vcc, exec, s[0:1]
	v_mov_b64_e32 v[2:3], 0
	v_mov_b64_e32 v[4:5], 0
	v_mov_b64_e32 v[6:7], 0
	v_mov_b64_e32 v[8:9], 0
	v_mov_b64_e32 v[10:11], 0
	v_mov_b64_e32 v[12:13], 0
	v_mov_b64_e32 v[14:15], 0
	v_mov_b64_e32 v[16:17], 0
	v_mov_b64_e32 v[18:19], 0
	v_mov_b64_e32 v[20:21], 0
	v_mov_b64_e32 v[22:23], 0
	v_mov_b64_e32 v[24:25], 0
	v_mov_b64_e32 v[26:27], 0
	v_mov_b64_e32 v[28:29], 0
	v_mov_b64_e32 v[30:31], 0
	v_mov_b64_e32 v[32:33], 0
	v_mov_b64_e32 v[34:35], 0
	v_mov_b64_e32 v[36:37], 0
	v_mov_b64_e32 v[38:39], 0
	v_mov_b64_e32 v[40:41], 0
	v_mov_b64_e32 v[42:43], 0
	v_mov_b64_e32 v[44:45], 0
	v_mov_b64_e32 v[46:47], 0
	v_mov_b64_e32 v[48:49], 0
	v_mov_b64_e32 v[50:51], 0
	v_mov_b64_e32 v[52:53], 0
	v_mov_b64_e32 v[54:55], 0
	v_mov_b64_e32 v[56:57], 0
	v_mov_b64_e32 v[58:59], 0
	v_mov_b64_e32 v[60:61], 0
	v_mov_b64_e32 v[62:63], 0
	v_mov_b64_e32 v[64:65], 0
	v_mov_b64_e32 v[66:67], 0
	v_mov_b64_e32 v[68:69], 0
	v_mov_b64_e32 v[70:71], 0
	v_mov_b64_e32 v[72:73], 0
	v_mov_b64_e32 v[74:75], 0
	v_mov_b64_e32 v[76:77], 0
	v_mov_b64_e32 v[78:79], 0
	v_mov_b64_e32 v[80:81], 0
	v_mov_b64_e32 v[82:83], 0
	v_mov_b64_e32 v[84:85], 0
	v_mov_b64_e32 v[86:87], 0
	v_mov_b64_e32 v[88:89], 0
	v_mov_b64_e32 v[90:91], 0
	v_mov_b64_e32 v[92:93], 0
	v_mov_b64_e32 v[94:95], 0
	v_mov_b64_e32 v[96:97], 0
	v_mov_b64_e32 v[98:99], 0
	v_mov_b64_e32 v[100:101], 0
	v_mov_b64_e32 v[102:103], 0
	v_mov_b64_e32 v[104:105], 0
	v_mov_b64_e32 v[106:107], 0
	v_mov_b64_e32 v[108:109], 0
	v_mov_b64_e32 v[110:111], 0
	v_mov_b64_e32 v[112:113], 0
	v_mov_b64_e32 v[114:115], 0
	v_mov_b64_e32 v[116:117], 0
	v_mov_b64_e32 v[118:119], 0
	v_mov_b64_e32 v[120:121], 0
	v_mov_b64_e32 v[122:123], 0
	v_mov_b64_e32 v[124:125], 0
	v_mov_b64_e32 v[126:127], 0
	v_mov_b64_e32 v[128:129], 0
	s_cbranch_vccnz .LBB0_2320
